# o20 plus nt cache hint on FF1 H stores
# speedup vs baseline: 1.0168x; 1.0168x over previous
; __device__ __forceinline__ int lane_id() { int l; asm volatile("v_mbcnt_lo_u32_b32 %0, -1, 0\n\tv_mbcnt_hi_u32_b32 %0, -1, %0" : "=v"(l)); return l; }
; __device__ __forceinline__ u32x4 pack8(const f32x4& a, const f32x4& b) { u32x4 w; w.x = cvt_pk_bf16(a[0], a[1]); w.y = cvt_pk_bf16(a[2], a[3]); w.z = cvt_pk_bf16(b[0], b[1]); w.w = cvt_pk_bf16(b[2], b[3]); return w; }
; #define PG8_SH_LDS(sh) do { PG8_LAS const unsigned char* sq_ = slds + RSTAT_OFF + 4096 + (u.ui & 1) * 1024 + (wc * 32 + 8 * fq) * 4; \
;     _Pragma("unroll") for (int bj = 0; bj < 2; ++bj) _Pragma("unroll") for (int n = 0; n < 2; ++n) sh[bj][n] = *(PG8_LAS const f32x4*)(sq_ + (bj * HALF + 4 * n) * 4); } while (0)
; #define PG8_RSTD8_LDS(rsv) do { PG8_LAS const unsigned char* sp_ = slds + RSTAT_OFF + (u.ui & 1) * 2048 + (wr * 64 + fr) * 8; \
;     _Pragma("unroll") for (int ai = 0; ai < 2; ++ai) _Pragma("unroll") for (int m = 0; m < 4; ++m) rsv[ai][m] = *(PG8_LAS const float*)(sp_ + (ai * 128 + m * 16) * 8); } while (0)
;     __device__ __forceinline__ void operator()(const f32x4 (&acc)[2][2][4][2], const Unit& u, int wr, int wc, int fr, int fq) const {
;         { const int l_ = lane_id(); fr = l_ & 15; fq = l_ >> 4; }
;         const int b = u.pm >> 3, c0 = u.pn * BM + wc * 32 + 8 * fq;
;         f32x4 sh[2][2]; PG8_SH_LDS(sh);
;         float rsv[2][4]; PG8_RSTD8_LDS(rsv);
; #pragma unroll
;         for (int ai = 0; ai < 2; ++ai)
; #pragma unroll
;             for (int m = 0; m < 4; ++m) { const int row = PG8_ROW(u, ai, m); const float rs = rsv[ai][m];
; #pragma unroll
;                 for (int bj = 0; bj < 2; ++bj) { f32x4 v0 = acc[ai][bj][m][0] * rs + sh[bj][0], v1 = acc[ai][bj][m][1] * rs + sh[bj][1];
; #pragma unroll
;                     for (int i = 0; i < 4; ++i) { const float a = fmaxf(v0[i], 0.f), c = fmaxf(v1[i], 0.f); v0[i] = a * a; v1[i] = c * c; }
;                     stb(H, (unsigned)((row * DFF + c0 + bj * HALF) * 2), pack8(v0, v1)); } }
;     }
.LBB13_1081:
	v_mbcnt_lo_u32_b32 v164, -1, 0
	v_mbcnt_hi_u32_b32 v164, -1, v164
	s_lshl_b32 s19, s56, 10
	v_ashrrev_i32_e32 v142, 1, v164
	s_lshl_b32 s21, s56, 11
	v_and_b32_e32 v174, -8, v142
	s_and_b32 s19, s19, 0x400
	s_and_b32 s21, s21, 0x800
	s_add_i32 s19, s19, 0
	v_add_u32_e32 v142, s49, v174
	s_add_i32 s21, s21, 0
	v_and_or_b32 v175, v164, 15, s48
	v_lshl_add_u32 v142, v142, 2, s19
	v_lshl_add_u32 v164, v175, 3, s21
	v_add_u32_e32 v142, 0x22800, v142
	v_add_u32_e32 v164, 0x21800, v164
	ds_read_b128 v[154:157], v142
	ds_read_b128 v[150:153], v142 offset:16
	ds_read_b128 v[146:149], v142 offset:512
	ds_read_b128 v[142:145], v142 offset:528
	ds_read2_b32 v[176:177], v164 offset1:32
	ds_read2_b32 v[178:179], v164 offset0:64 offset1:96
	s_lshl_b32 s19, s28, 8
	s_or_b32 s19, s19, s49
	v_add_lshl_u32 v174, s19, v174, 1
	s_waitcnt lgkmcnt(0)
	v_pk_fma_f32 v[134:135], v[134:135], v[176:177], v[150:151] op_sel_hi:[1,0,1]
	s_lshl_b32 s19, s26, 21
	v_lshlrev_b32_e32 v175, 13, v175
	v_pk_fma_f32 v[138:139], v[138:139], v[176:177], v[154:155] op_sel_hi:[1,0,1]
	v_pk_fma_f32 v[136:137], v[136:137], v[176:177], v[152:153] op_sel_hi:[1,0,1]
	v_max_f32_e32 v134, 0, v134
	v_add3_u32 v174, v175, s19, v174
	v_pk_fma_f32 v[140:141], v[140:141], v[176:177], v[156:157] op_sel_hi:[1,0,1]
	v_mul_f32_e32 v175, v134, v134
	v_max_f32_e32 v134, 0, v139
	v_max_f32_e32 v135, 0, v135
	v_max_f32_e32 v136, 0, v136
	v_add_u32_e32 v164, 0x400, v164
	v_max_f32_e32 v138, 0, v138
	v_mul_f32_e32 v134, v134, v134
	v_mul_f32_e32 v139, v135, v135
	v_max_f32_e32 v135, 0, v140
	v_mul_f32_e32 v140, v136, v136
	v_max_f32_e32 v136, 0, v141
	v_max_f32_e32 v137, 0, v137
	v_pk_fma_f32 v[126:127], v[126:127], v[176:177], v[142:143] op_sel_hi:[1,0,1]
	ds_read2_b32 v[166:167], v164 offset1:32
	ds_read2_b32 v[164:165], v164 offset0:64 offset1:96
	v_mul_f32_e32 v138, v138, v138
	v_mul_f32_e32 v135, v135, v135
	v_mul_f32_e32 v136, v136, v136
	v_mul_f32_e32 v137, v137, v137
	v_cvt_pk_bf16_f32 v134, v138, v134
	v_pk_fma_f32 v[132:133], v[132:133], v[176:177], v[148:149] op_sel_hi:[1,0,1]
	v_pk_fma_f32 v[130:131], v[130:131], v[176:177], v[146:147] op_sel_hi:[1,0,1]
	v_pk_fma_f32 v[128:129], v[128:129], v[176:177], v[144:145] op_sel_hi:[1,0,1]
	v_max_f32_e32 v126, 0, v126
	v_max_f32_e32 v127, 0, v127
	v_cvt_pk_bf16_f32 v135, v135, v136
	v_cvt_pk_bf16_f32 v136, v175, v139
	v_cvt_pk_bf16_f32 v137, v140, v137
	global_store_dwordx4 v174, v[134:137], s[14:15] nt
	v_max_f32_e32 v128, 0, v128
	v_max_f32_e32 v130, 0, v130
	v_mul_f32_e32 v134, v126, v126
	v_max_f32_e32 v126, 0, v131
	v_mul_f32_e32 v131, v127, v127
	v_max_f32_e32 v127, 0, v132
	v_mul_f32_e32 v126, v126, v126
	v_mul_f32_e32 v127, v127, v127
	v_mul_f32_e32 v132, v128, v128
	v_max_f32_e32 v128, 0, v133
	v_max_f32_e32 v129, 0, v129
	v_mul_f32_e32 v130, v130, v130
	v_mul_f32_e32 v128, v128, v128
	v_mul_f32_e32 v129, v129, v129
	v_add_u32_e32 v133, 0x100, v174
	v_cvt_pk_bf16_f32 v126, v130, v126
	v_cvt_pk_bf16_f32 v127, v127, v128
	v_cvt_pk_bf16_f32 v128, v134, v131
	v_cvt_pk_bf16_f32 v129, v132, v129
	global_store_dwordx4 v133, v[126:129], s[14:15] nt
	v_pk_fma_f32 v[102:103], v[102:103], v[178:179], v[150:151] op_sel_hi:[1,0,1]
	v_pk_fma_f32 v[106:107], v[106:107], v[178:179], v[154:155] op_sel_hi:[1,0,1]
	v_add_u32_e32 v127, 0x20000, v174
	v_mov_b32_e32 v126, v177
	v_pk_fma_f32 v[118:119], v[118:119], v[126:127], v[150:151] op_sel_hi:[1,0,1]
	v_pk_fma_f32 v[122:123], v[122:123], v[126:127], v[154:155] op_sel_hi:[1,0,1]
	v_pk_fma_f32 v[120:121], v[120:121], v[126:127], v[152:153] op_sel_hi:[1,0,1]
	v_max_f32_e32 v118, 0, v118
	v_pk_fma_f32 v[124:125], v[124:125], v[126:127], v[156:157] op_sel_hi:[1,0,1]
	v_mul_f32_e32 v128, v118, v118
	v_max_f32_e32 v118, 0, v123
	v_max_f32_e32 v119, 0, v119
	v_max_f32_e32 v120, 0, v120
	v_max_f32_e32 v122, 0, v122
	v_mul_f32_e32 v118, v118, v118
	v_mul_f32_e32 v123, v119, v119
	v_max_f32_e32 v119, 0, v124
	v_mul_f32_e32 v124, v120, v120
	v_max_f32_e32 v120, 0, v125
	v_max_f32_e32 v121, 0, v121
	v_pk_fma_f32 v[110:111], v[110:111], v[126:127], v[142:143] op_sel_hi:[1,0,1]
	v_mul_f32_e32 v122, v122, v122
	v_mul_f32_e32 v119, v119, v119
	v_mul_f32_e32 v120, v120, v120
	v_mul_f32_e32 v121, v121, v121
	v_cvt_pk_bf16_f32 v118, v122, v118
	v_pk_fma_f32 v[116:117], v[116:117], v[126:127], v[148:149] op_sel_hi:[1,0,1]
	v_pk_fma_f32 v[114:115], v[114:115], v[126:127], v[146:147] op_sel_hi:[1,0,1]
	v_pk_fma_f32 v[112:113], v[112:113], v[126:127], v[144:145] op_sel_hi:[1,0,1]
	v_max_f32_e32 v110, 0, v110
	v_max_f32_e32 v111, 0, v111
	v_cvt_pk_bf16_f32 v119, v119, v120
	v_cvt_pk_bf16_f32 v120, v128, v123
	v_cvt_pk_bf16_f32 v121, v124, v121
	global_store_dwordx4 v127, v[118:121], s[14:15] nt
	v_max_f32_e32 v112, 0, v112
	v_max_f32_e32 v114, 0, v114
	v_mul_f32_e32 v118, v110, v110
	v_max_f32_e32 v110, 0, v115
	v_mul_f32_e32 v115, v111, v111
	v_max_f32_e32 v111, 0, v116
	v_mul_f32_e32 v110, v110, v110
	v_mul_f32_e32 v111, v111, v111
	v_mul_f32_e32 v116, v112, v112
	v_max_f32_e32 v112, 0, v117
	v_max_f32_e32 v113, 0, v113
	v_mul_f32_e32 v114, v114, v114
	v_mul_f32_e32 v112, v112, v112
	v_mul_f32_e32 v113, v113, v113
	v_add_u32_e32 v117, 0x20100, v174
	v_cvt_pk_bf16_f32 v110, v114, v110
	v_cvt_pk_bf16_f32 v111, v111, v112
	v_pk_fma_f32 v[104:105], v[104:105], v[178:179], v[152:153] op_sel_hi:[1,0,1]
	v_max_f32_e32 v102, 0, v102
	v_cvt_pk_bf16_f32 v112, v118, v115
	v_cvt_pk_bf16_f32 v113, v116, v113
	global_store_dwordx4 v117, v[110:113], s[14:15] nt
	v_pk_fma_f32 v[108:109], v[108:109], v[178:179], v[156:157] op_sel_hi:[1,0,1]
	v_max_f32_e32 v103, 0, v103
	v_mul_f32_e32 v111, v102, v102
	v_max_f32_e32 v102, 0, v107
; __device__ __forceinline__ u32x4 pack8(const f32x4& a, const f32x4& b) { u32x4 w; w.x = cvt_pk_bf16(a[0], a[1]); w.y = cvt_pk_bf16(a[2], a[3]); w.z = cvt_pk_bf16(b[0], b[1]); w.w = cvt_pk_bf16(b[2], b[3]); return w; }
;     __device__ __forceinline__ void operator()(const f32x4 (&acc)[2][2][4][2], const Unit& u, int wr, int wc, int fr, int fq) const {
;     ...
;             for (int m = 0; m < 4; ++m) { const int row = PG8_ROW(u, ai, m); const float rs = rsv[ai][m];
; #pragma unroll
;                 for (int bj = 0; bj < 2; ++bj) { f32x4 v0 = acc[ai][bj][m][0] * rs + sh[bj][0], v1 = acc[ai][bj][m][1] * rs + sh[bj][1];
; #pragma unroll
;                     for (int i = 0; i < 4; ++i) { const float a = fmaxf(v0[i], 0.f), c = fmaxf(v1[i], 0.f); v0[i] = a * a; v1[i] = c * c; }
;                     stb(H, (unsigned)((row * DFF + c0 + bj * HALF) * 2), pack8(v0, v1)); } }
	v_max_f32_e32 v104, 0, v104
	v_max_f32_e32 v106, 0, v106
	v_mul_f32_e32 v102, v102, v102
	v_mul_f32_e32 v107, v103, v103
	v_max_f32_e32 v103, 0, v108
	v_mul_f32_e32 v108, v104, v104
	v_max_f32_e32 v104, 0, v109
	v_max_f32_e32 v105, 0, v105
	v_pk_fma_f32 v[94:95], v[94:95], v[178:179], v[142:143] op_sel_hi:[1,0,1]
	v_add_u32_e32 v110, 0x40000, v174
	v_mul_f32_e32 v106, v106, v106
	v_mul_f32_e32 v103, v103, v103
	v_mul_f32_e32 v104, v104, v104
	v_mul_f32_e32 v105, v105, v105
	v_cvt_pk_bf16_f32 v102, v106, v102
	v_pk_fma_f32 v[100:101], v[100:101], v[178:179], v[148:149] op_sel_hi:[1,0,1]
	v_pk_fma_f32 v[98:99], v[98:99], v[178:179], v[146:147] op_sel_hi:[1,0,1]
	v_pk_fma_f32 v[96:97], v[96:97], v[178:179], v[144:145] op_sel_hi:[1,0,1]
	v_max_f32_e32 v94, 0, v94
	v_max_f32_e32 v95, 0, v95
	v_cvt_pk_bf16_f32 v103, v103, v104
	v_cvt_pk_bf16_f32 v104, v111, v107
	v_cvt_pk_bf16_f32 v105, v108, v105
	global_store_dwordx4 v110, v[102:105], s[14:15] nt
	v_max_f32_e32 v96, 0, v96
	v_max_f32_e32 v98, 0, v98
	v_mul_f32_e32 v102, v94, v94
	v_max_f32_e32 v94, 0, v99
	v_mul_f32_e32 v99, v95, v95
	v_max_f32_e32 v95, 0, v100
	v_mul_f32_e32 v94, v94, v94
	v_mul_f32_e32 v95, v95, v95
	v_mul_f32_e32 v100, v96, v96
	v_max_f32_e32 v96, 0, v101
	v_max_f32_e32 v97, 0, v97
	v_mul_f32_e32 v98, v98, v98
	v_mul_f32_e32 v96, v96, v96
	v_mul_f32_e32 v97, v97, v97
	v_add_u32_e32 v101, 0x40100, v174
	v_cvt_pk_bf16_f32 v94, v98, v94
	v_cvt_pk_bf16_f32 v95, v95, v96
	v_cvt_pk_bf16_f32 v96, v102, v99
	v_cvt_pk_bf16_f32 v97, v100, v97
	global_store_dwordx4 v101, v[94:97], s[14:15] nt
	s_waitcnt lgkmcnt(0)
	v_pk_fma_f32 v[70:71], v[70:71], v[166:167], v[150:151] op_sel_hi:[1,0,1]
	v_pk_fma_f32 v[74:75], v[74:75], v[166:167], v[154:155] op_sel_hi:[1,0,1]
	v_add_u32_e32 v95, 0x60000, v174
	v_mov_b32_e32 v94, v179
	v_pk_fma_f32 v[86:87], v[86:87], v[94:95], v[150:151] op_sel_hi:[1,0,1]
	v_pk_fma_f32 v[90:91], v[90:91], v[94:95], v[154:155] op_sel_hi:[1,0,1]
	v_pk_fma_f32 v[88:89], v[88:89], v[94:95], v[152:153] op_sel_hi:[1,0,1]
	v_max_f32_e32 v86, 0, v86
	v_pk_fma_f32 v[92:93], v[92:93], v[94:95], v[156:157] op_sel_hi:[1,0,1]
	v_mul_f32_e32 v96, v86, v86
	v_max_f32_e32 v86, 0, v91
	v_max_f32_e32 v87, 0, v87
	v_max_f32_e32 v88, 0, v88
	v_max_f32_e32 v90, 0, v90
	v_mul_f32_e32 v86, v86, v86
	v_mul_f32_e32 v91, v87, v87
	v_max_f32_e32 v87, 0, v92
	v_mul_f32_e32 v92, v88, v88
	v_max_f32_e32 v88, 0, v93
	v_max_f32_e32 v89, 0, v89
	v_pk_fma_f32 v[78:79], v[78:79], v[94:95], v[142:143] op_sel_hi:[1,0,1]
	v_mul_f32_e32 v90, v90, v90
	v_mul_f32_e32 v87, v87, v87
	v_mul_f32_e32 v88, v88, v88
	v_mul_f32_e32 v89, v89, v89
	v_cvt_pk_bf16_f32 v86, v90, v86
	v_pk_fma_f32 v[84:85], v[84:85], v[94:95], v[148:149] op_sel_hi:[1,0,1]
	v_pk_fma_f32 v[82:83], v[82:83], v[94:95], v[146:147] op_sel_hi:[1,0,1]
	v_pk_fma_f32 v[80:81], v[80:81], v[94:95], v[144:145] op_sel_hi:[1,0,1]
	v_max_f32_e32 v78, 0, v78
	v_max_f32_e32 v79, 0, v79
	v_cvt_pk_bf16_f32 v87, v87, v88
	v_cvt_pk_bf16_f32 v88, v96, v91
	v_cvt_pk_bf16_f32 v89, v92, v89
	global_store_dwordx4 v95, v[86:89], s[14:15] nt
	v_max_f32_e32 v80, 0, v80
	v_max_f32_e32 v82, 0, v82
	v_mul_f32_e32 v86, v78, v78
	v_max_f32_e32 v78, 0, v83
	v_mul_f32_e32 v83, v79, v79
	v_max_f32_e32 v79, 0, v84
	v_mul_f32_e32 v78, v78, v78
	v_mul_f32_e32 v79, v79, v79
	v_mul_f32_e32 v84, v80, v80
	v_max_f32_e32 v80, 0, v85
	v_max_f32_e32 v81, 0, v81
	v_mul_f32_e32 v82, v82, v82
	v_mul_f32_e32 v80, v80, v80
	v_mul_f32_e32 v81, v81, v81
	v_add_u32_e32 v85, 0x60100, v174
	v_cvt_pk_bf16_f32 v78, v82, v78
	v_cvt_pk_bf16_f32 v79, v79, v80
	v_pk_fma_f32 v[72:73], v[72:73], v[166:167], v[152:153] op_sel_hi:[1,0,1]
	v_max_f32_e32 v70, 0, v70
	v_cvt_pk_bf16_f32 v80, v86, v83
	v_cvt_pk_bf16_f32 v81, v84, v81
	global_store_dwordx4 v85, v[78:81], s[14:15] nt
	v_pk_fma_f32 v[76:77], v[76:77], v[166:167], v[156:157] op_sel_hi:[1,0,1]
	v_max_f32_e32 v71, 0, v71
	v_mul_f32_e32 v79, v70, v70
	v_max_f32_e32 v70, 0, v75
	v_max_f32_e32 v72, 0, v72
	v_max_f32_e32 v74, 0, v74
	v_mul_f32_e32 v70, v70, v70
	v_mul_f32_e32 v75, v71, v71
	v_max_f32_e32 v71, 0, v76
	v_mul_f32_e32 v76, v72, v72
	v_max_f32_e32 v72, 0, v77
	v_max_f32_e32 v73, 0, v73
	v_pk_fma_f32 v[62:63], v[62:63], v[166:167], v[142:143] op_sel_hi:[1,0,1]
	v_add_u32_e32 v78, 0x100000, v174
	v_mul_f32_e32 v74, v74, v74
	v_mul_f32_e32 v71, v71, v71
	v_mul_f32_e32 v72, v72, v72
	v_mul_f32_e32 v73, v73, v73
	v_cvt_pk_bf16_f32 v70, v74, v70
	v_pk_fma_f32 v[68:69], v[68:69], v[166:167], v[148:149] op_sel_hi:[1,0,1]
	v_pk_fma_f32 v[66:67], v[66:67], v[166:167], v[146:147] op_sel_hi:[1,0,1]
	v_pk_fma_f32 v[64:65], v[64:65], v[166:167], v[144:145] op_sel_hi:[1,0,1]
	v_max_f32_e32 v62, 0, v62
	v_max_f32_e32 v63, 0, v63
	v_cvt_pk_bf16_f32 v71, v71, v72
	v_cvt_pk_bf16_f32 v72, v79, v75
	v_cvt_pk_bf16_f32 v73, v76, v73
	global_store_dwordx4 v78, v[70:73], s[14:15] nt
	v_max_f32_e32 v64, 0, v64
	v_max_f32_e32 v66, 0, v66
	v_mul_f32_e32 v70, v62, v62
	v_max_f32_e32 v62, 0, v67
	v_mul_f32_e32 v67, v63, v63
	v_max_f32_e32 v63, 0, v68
	v_mul_f32_e32 v62, v62, v62
	v_mul_f32_e32 v63, v63, v63
	v_mul_f32_e32 v68, v64, v64
	v_max_f32_e32 v64, 0, v69
	v_max_f32_e32 v65, 0, v65
	v_mul_f32_e32 v66, v66, v66
	v_mul_f32_e32 v64, v64, v64
	v_mul_f32_e32 v65, v65, v65
	v_add_u32_e32 v69, 0x100100, v174
	v_cvt_pk_bf16_f32 v62, v66, v62
	v_cvt_pk_bf16_f32 v63, v63, v64
	v_cvt_pk_bf16_f32 v64, v70, v67
	v_cvt_pk_bf16_f32 v65, v68, v65
	global_store_dwordx4 v69, v[62:65], s[14:15] nt
	v_pk_fma_f32 v[38:39], v[38:39], v[164:165], v[150:151] op_sel_hi:[1,0,1]
	v_pk_fma_f32 v[42:43], v[42:43], v[164:165], v[154:155] op_sel_hi:[1,0,1]
	v_add_u32_e32 v63, 0x120000, v174
; __device__ __forceinline__ u32x4 pack8(const f32x4& a, const f32x4& b) { u32x4 w; w.x = cvt_pk_bf16(a[0], a[1]); w.y = cvt_pk_bf16(a[2], a[3]); w.z = cvt_pk_bf16(b[0], b[1]); w.w = cvt_pk_bf16(b[2], b[3]); return w; }
;     __device__ __forceinline__ void operator()(const f32x4 (&acc)[2][2][4][2], const Unit& u, int wr, int wc, int fr, int fq) const {
;     ...
;             for (int m = 0; m < 4; ++m) { const int row = PG8_ROW(u, ai, m); const float rs = rsv[ai][m];
; #pragma unroll
;                 for (int bj = 0; bj < 2; ++bj) { f32x4 v0 = acc[ai][bj][m][0] * rs + sh[bj][0], v1 = acc[ai][bj][m][1] * rs + sh[bj][1];
; #pragma unroll
;                     for (int i = 0; i < 4; ++i) { const float a = fmaxf(v0[i], 0.f), c = fmaxf(v1[i], 0.f); v0[i] = a * a; v1[i] = c * c; }
;                     stb(H, (unsigned)((row * DFF + c0 + bj * HALF) * 2), pack8(v0, v1)); } }
;     }
	v_mov_b32_e32 v62, v167
	v_pk_fma_f32 v[54:55], v[54:55], v[62:63], v[150:151] op_sel_hi:[1,0,1]
	v_pk_fma_f32 v[58:59], v[58:59], v[62:63], v[154:155] op_sel_hi:[1,0,1]
	v_pk_fma_f32 v[56:57], v[56:57], v[62:63], v[152:153] op_sel_hi:[1,0,1]
	v_max_f32_e32 v54, 0, v54
	v_pk_fma_f32 v[60:61], v[60:61], v[62:63], v[156:157] op_sel_hi:[1,0,1]
	v_mul_f32_e32 v64, v54, v54
	v_max_f32_e32 v54, 0, v59
	v_max_f32_e32 v55, 0, v55
	v_max_f32_e32 v56, 0, v56
	v_max_f32_e32 v58, 0, v58
	v_mul_f32_e32 v54, v54, v54
	v_mul_f32_e32 v59, v55, v55
	v_max_f32_e32 v55, 0, v60
	v_mul_f32_e32 v60, v56, v56
	v_max_f32_e32 v56, 0, v61
	v_max_f32_e32 v57, 0, v57
	v_pk_fma_f32 v[46:47], v[46:47], v[62:63], v[142:143] op_sel_hi:[1,0,1]
	v_mul_f32_e32 v58, v58, v58
	v_mul_f32_e32 v55, v55, v55
	v_mul_f32_e32 v56, v56, v56
	v_mul_f32_e32 v57, v57, v57
	v_cvt_pk_bf16_f32 v54, v58, v54
	v_pk_fma_f32 v[52:53], v[52:53], v[62:63], v[148:149] op_sel_hi:[1,0,1]
	v_pk_fma_f32 v[50:51], v[50:51], v[62:63], v[146:147] op_sel_hi:[1,0,1]
	v_pk_fma_f32 v[48:49], v[48:49], v[62:63], v[144:145] op_sel_hi:[1,0,1]
	v_max_f32_e32 v46, 0, v46
	v_max_f32_e32 v47, 0, v47
	v_cvt_pk_bf16_f32 v55, v55, v56
	v_cvt_pk_bf16_f32 v56, v64, v59
	v_cvt_pk_bf16_f32 v57, v60, v57
	global_store_dwordx4 v63, v[54:57], s[14:15] nt
	v_max_f32_e32 v48, 0, v48
	v_max_f32_e32 v50, 0, v50
	v_mul_f32_e32 v54, v46, v46
	v_max_f32_e32 v46, 0, v51
	v_mul_f32_e32 v51, v47, v47
	v_max_f32_e32 v47, 0, v52
	v_mul_f32_e32 v46, v46, v46
	v_mul_f32_e32 v47, v47, v47
	v_mul_f32_e32 v52, v48, v48
	v_max_f32_e32 v48, 0, v53
	v_max_f32_e32 v49, 0, v49
	v_mul_f32_e32 v50, v50, v50
	v_mul_f32_e32 v48, v48, v48
	v_mul_f32_e32 v49, v49, v49
	v_add_u32_e32 v53, 0x120100, v174
	v_cvt_pk_bf16_f32 v46, v50, v46
	v_cvt_pk_bf16_f32 v47, v47, v48
	v_pk_fma_f32 v[40:41], v[40:41], v[164:165], v[152:153] op_sel_hi:[1,0,1]
	v_max_f32_e32 v38, 0, v38
	v_cvt_pk_bf16_f32 v48, v54, v51
	v_cvt_pk_bf16_f32 v49, v52, v49
	global_store_dwordx4 v53, v[46:49], s[14:15] nt
	v_pk_fma_f32 v[44:45], v[44:45], v[164:165], v[156:157] op_sel_hi:[1,0,1]
	v_max_f32_e32 v39, 0, v39
	v_mul_f32_e32 v47, v38, v38
	v_max_f32_e32 v38, 0, v43
	v_max_f32_e32 v40, 0, v40
	v_max_f32_e32 v42, 0, v42
	v_mul_f32_e32 v38, v38, v38
	v_mul_f32_e32 v43, v39, v39
	v_max_f32_e32 v39, 0, v44
	v_mul_f32_e32 v44, v40, v40
	v_max_f32_e32 v40, 0, v45
	v_max_f32_e32 v41, 0, v41
	v_pk_fma_f32 v[30:31], v[30:31], v[164:165], v[142:143] op_sel_hi:[1,0,1]
	v_add_u32_e32 v46, 0x140000, v174
	v_mul_f32_e32 v42, v42, v42
	v_mul_f32_e32 v39, v39, v39
	v_mul_f32_e32 v40, v40, v40
	v_mul_f32_e32 v41, v41, v41
	v_cvt_pk_bf16_f32 v38, v42, v38
	v_pk_fma_f32 v[36:37], v[36:37], v[164:165], v[148:149] op_sel_hi:[1,0,1]
	v_pk_fma_f32 v[34:35], v[34:35], v[164:165], v[146:147] op_sel_hi:[1,0,1]
	v_pk_fma_f32 v[32:33], v[32:33], v[164:165], v[144:145] op_sel_hi:[1,0,1]
	v_max_f32_e32 v30, 0, v30
	v_max_f32_e32 v31, 0, v31
	v_cvt_pk_bf16_f32 v39, v39, v40
	v_cvt_pk_bf16_f32 v40, v47, v43
	v_cvt_pk_bf16_f32 v41, v44, v41
	global_store_dwordx4 v46, v[38:41], s[14:15] nt
	v_max_f32_e32 v32, 0, v32
	v_max_f32_e32 v34, 0, v34
	v_mul_f32_e32 v38, v30, v30
	v_max_f32_e32 v30, 0, v35
	v_mul_f32_e32 v35, v31, v31
	v_max_f32_e32 v31, 0, v36
	v_mul_f32_e32 v30, v30, v30
	v_mul_f32_e32 v31, v31, v31
	v_mul_f32_e32 v36, v32, v32
	v_max_f32_e32 v32, 0, v37
	v_max_f32_e32 v33, 0, v33
	v_mul_f32_e32 v34, v34, v34
	v_mul_f32_e32 v32, v32, v32
	v_mul_f32_e32 v33, v33, v33
	v_add_u32_e32 v37, 0x140100, v174
	v_cvt_pk_bf16_f32 v30, v34, v30
	v_cvt_pk_bf16_f32 v31, v31, v32
	v_cvt_pk_bf16_f32 v32, v38, v35
	v_cvt_pk_bf16_f32 v33, v36, v33
	global_store_dwordx4 v37, v[30:33], s[14:15] nt
	s_and_b64 vcc, exec, s[8:9]
	s_mov_b64 s[8:9], -1
	v_add_u32_e32 v31, 0x160000, v174
	v_mov_b32_e32 v30, v165
	v_pk_fma_f32 v[22:23], v[22:23], v[30:31], v[150:151] op_sel_hi:[1,0,1]
	v_pk_fma_f32 v[26:27], v[26:27], v[30:31], v[154:155] op_sel_hi:[1,0,1]
	v_pk_fma_f32 v[24:25], v[24:25], v[30:31], v[152:153] op_sel_hi:[1,0,1]
	v_max_f32_e32 v22, 0, v22
	v_pk_fma_f32 v[28:29], v[28:29], v[30:31], v[156:157] op_sel_hi:[1,0,1]
	v_mul_f32_e32 v32, v22, v22
	v_max_f32_e32 v22, 0, v27
	v_max_f32_e32 v23, 0, v23
	v_max_f32_e32 v24, 0, v24
	v_max_f32_e32 v26, 0, v26
	v_mul_f32_e32 v22, v22, v22
	v_mul_f32_e32 v27, v23, v23
	v_max_f32_e32 v23, 0, v28
	v_mul_f32_e32 v28, v24, v24
	v_max_f32_e32 v24, 0, v29
	v_max_f32_e32 v25, 0, v25
	v_pk_fma_f32 v[16:17], v[16:17], v[30:31], v[144:145] op_sel_hi:[1,0,1]
	v_pk_fma_f32 v[14:15], v[14:15], v[30:31], v[142:143] op_sel_hi:[1,0,1]
	v_mul_f32_e32 v26, v26, v26
	v_mul_f32_e32 v23, v23, v23
	v_mul_f32_e32 v24, v24, v24
	v_mul_f32_e32 v25, v25, v25
	v_cvt_pk_bf16_f32 v22, v26, v22
	v_pk_fma_f32 v[20:21], v[20:21], v[30:31], v[148:149] op_sel_hi:[1,0,1]
	v_pk_fma_f32 v[18:19], v[18:19], v[30:31], v[146:147] op_sel_hi:[1,0,1]
	v_max_f32_e32 v14, 0, v14
	v_max_f32_e32 v15, 0, v15
	v_max_f32_e32 v16, 0, v16
	v_cvt_pk_bf16_f32 v23, v23, v24
	v_cvt_pk_bf16_f32 v24, v32, v27
	v_cvt_pk_bf16_f32 v25, v28, v25
	global_store_dwordx4 v31, v[22:25], s[14:15] nt
	v_max_f32_e32 v17, 0, v17
	v_max_f32_e32 v18, 0, v18
	v_mul_f32_e32 v22, v14, v14
	v_max_f32_e32 v14, 0, v19
	v_mul_f32_e32 v19, v15, v15
	v_max_f32_e32 v15, 0, v20
	v_mul_f32_e32 v20, v16, v16
	v_max_f32_e32 v16, 0, v21
	v_mul_f32_e32 v14, v14, v14
	v_mul_f32_e32 v15, v15, v15
	v_mul_f32_e32 v16, v16, v16
	v_mul_f32_e32 v17, v17, v17
	v_add_u32_e32 v21, 0x160100, v174
	v_mul_f32_e32 v18, v18, v18
	v_cvt_pk_bf16_f32 v14, v18, v14
	v_cvt_pk_bf16_f32 v15, v15, v16
	v_cvt_pk_bf16_f32 v16, v22, v19
	v_cvt_pk_bf16_f32 v17, v20, v17
	global_store_dwordx4 v21, v[14:17], s[14:15] nt
	s_cbranch_vccnz .LBB13_1066
	s_andn2_b64 vcc, exec, s[12:13]
	s_cbranch_vccnz .LBB13_1065
	s_barrier
	s_branch .LBB13_1065
